# attention tile loop: 45 packed-f32 VOP3P ops (v_pk_add/mul_f32) split into scalar pairs, 20 dst-forwarding s_nop 0 dropped (bit-identical)
# speedup vs baseline: 1.0061x; 1.0049x over previous
.LBB0_873:
	s_cmpk_eq_i32 s71, 0xffd0
	s_cselect_b64 s[34:35], -1, 0
	s_and_b64 s[4:5], s[34:35], exec
	s_cselect_b32 s84, 0, s71
	s_cmp_gt_i32 s84, s29
	s_cselect_b64 s[4:5], -1, 0
	s_or_b64 s[4:5], s[58:59], s[4:5]
	s_and_b64 vcc, exec, s[4:5]
	s_cbranch_vccnz .LBB0_883
	ds_read_b128 v[88:91], v221
	ds_read_b128 v[92:95], v221 offset:64
	s_add_i32 s4, s84, 63
	s_cmp_gt_i32 s4, s95
	s_cselect_b64 s[4:5], -1, 0
	s_waitcnt lgkmcnt(1)
	v_mfma_f32_16x16x32_bf16 v[96:99], v[88:91], v[0:3], 0
	s_or_b64 s[74:75], s[34:35], s[4:5]
	s_cmpk_lg_i32 s71, 0xffd0
	s_mov_b64 s[34:35], -1
	v_mfma_f32_16x16x32_bf16 v[88:91], v[88:91], v[8:11], 0
	s_cselect_b64 s[72:73], -1, 0
	s_and_b64 vcc, exec, s[74:75]
	s_waitcnt lgkmcnt(0)
	v_mfma_f32_16x16x32_bf16 v[116:119], v[92:95], v[4:7], v[96:99]
	v_mfma_f32_16x16x32_bf16 v[100:103], v[92:95], v[12:15], v[88:91]
	s_nop 2
	ds_read_b128 v[88:91], v221 offset:576
	ds_read_b128 v[92:95], v221 offset:640
	s_waitcnt lgkmcnt(1)
	v_mfma_f32_16x16x32_bf16 v[96:99], v[88:91], v[0:3], 0
	v_mfma_f32_16x16x32_bf16 v[88:91], v[88:91], v[8:11], 0
	s_waitcnt lgkmcnt(0)
	v_mfma_f32_16x16x32_bf16 v[112:115], v[92:95], v[4:7], v[96:99]
	v_mfma_f32_16x16x32_bf16 v[96:99], v[92:95], v[12:15], v[88:91]
	s_nop 4
	ds_read_b128 v[88:91], v221 offset:4608
	ds_read_b128 v[92:95], v221 offset:4672
	s_waitcnt lgkmcnt(1)
	v_mfma_f32_16x16x32_bf16 v[104:107], v[88:91], v[0:3], 0
	v_mfma_f32_16x16x32_bf16 v[88:91], v[88:91], v[8:11], 0
	s_waitcnt lgkmcnt(0)
	v_mfma_f32_16x16x32_bf16 v[108:111], v[92:95], v[4:7], v[104:107]
	v_mfma_f32_16x16x32_bf16 v[92:95], v[92:95], v[12:15], v[88:91]
	s_nop 4
	ds_read_b128 v[88:91], v221 offset:5184
	ds_read_b128 v[160:163], v221 offset:5248
	s_waitcnt lgkmcnt(1)
	v_mfma_f32_16x16x32_bf16 v[104:107], v[88:91], v[0:3], 0
	v_mfma_f32_16x16x32_bf16 v[88:91], v[88:91], v[8:11], 0
	s_waitcnt lgkmcnt(0)
	v_mfma_f32_16x16x32_bf16 v[104:107], v[160:163], v[4:7], v[104:107]
	v_mfma_f32_16x16x32_bf16 v[88:91], v[160:163], v[12:15], v[88:91]
	s_cbranch_vccnz .LBB0_876
	v_sub_f32_e32 v160, v140, v84
	v_sub_f32_e32 v161, v141, v85
	v_sub_f32_e32 v162, v140, v86
	v_sub_f32_e32 v163, v141, v87
	v_add_f32_e32 v160, v160, v116
	v_add_f32_e32 v161, v161, v117
	v_add_f32_e32 v162, v162, v118
	v_add_f32_e32 v163, v163, v119
	v_max3_f32 v164, v160, s86, v161
	v_max3_f32 v166, v164, v162, v163
	v_sub_f32_e32 v164, v140, v76
	v_sub_f32_e32 v165, v141, v77
	s_mov_b64 s[34:35], 0
	v_add_f32_e32 v164, v164, v112
	v_add_f32_e32 v165, v165, v113
	v_max3_f32 v170, v166, v164, v165
	v_sub_f32_e32 v166, v140, v78
	v_sub_f32_e32 v167, v141, v79
	v_add_f32_e32 v168, v166, v114
	v_add_f32_e32 v169, v167, v115
	v_sub_f32_e32 v166, v140, v80
	v_sub_f32_e32 v167, v141, v81
	v_max3_f32 v170, v170, v168, v169
	v_add_f32_e32 v166, v166, v108
	v_add_f32_e32 v167, v167, v109
	v_max3_f32 v172, v170, v166, v167
	v_sub_f32_e32 v170, v140, v82
	v_sub_f32_e32 v171, v141, v83
	v_add_f32_e32 v170, v170, v110
	v_add_f32_e32 v171, v171, v111
	v_max3_f32 v174, v172, v170, v171
	v_sub_f32_e32 v172, v140, v72
	v_sub_f32_e32 v173, v141, v73
	v_add_f32_e32 v172, v172, v104
	v_add_f32_e32 v173, v173, v105
	v_max3_f32 v202, v174, v172, v173
	v_sub_f32_e32 v174, v140, v74
	v_sub_f32_e32 v175, v141, v75
	v_add_f32_e32 v174, v174, v106
	v_add_f32_e32 v175, v175, v107
	v_max3_f32 v230, v202, v174, v175

.LBB0_878:
	s_nop 3
	v_and_b32_e32 v105, 64, v183
	v_xor_b32_e32 v104, 16, v183
	v_add_u32_e32 v105, 64, v105
	v_cmp_lt_i32_e32 vcc, v104, v105
	v_xor_b32_e32 v106, 32, v183
	s_xor_b64 s[4:5], s[74:75], -1
	v_cndmask_b32_e32 v104, v183, v104, vcc
	v_lshlrev_b32_e32 v229, 2, v104
	ds_bpermute_b32 v104, v229, v230
	v_cmp_lt_i32_e32 vcc, v106, v105
	s_mov_b64 s[34:35], -1
	s_waitcnt lgkmcnt(0)
	v_max_f32_e32 v104, v104, v104
	v_cndmask_b32_e32 v105, v183, v106, vcc
	v_lshlrev_b32_e32 v228, 2, v105
	v_max_f32_e32 v105, v230, v230
	v_max_f32_e32 v231, v105, v104
	ds_bpermute_b32 v232, v228, v231
	s_andn2_b64 vcc, exec, s[4:5]
	s_cbranch_vccnz .LBB0_880
	v_sub_f32_e32 v104, v142, v84
	v_sub_f32_e32 v105, v143, v85
	v_sub_f32_e32 v106, v142, v86
	v_sub_f32_e32 v107, v143, v87
	v_add_f32_e32 v104, v104, v100
	v_add_f32_e32 v105, v105, v101
	v_add_f32_e32 v106, v106, v102
	v_add_f32_e32 v107, v107, v103
	v_max3_f32 v108, v104, s86, v105
	v_max3_f32 v110, v108, v106, v107
	v_sub_f32_e32 v108, v142, v76
	v_sub_f32_e32 v109, v143, v77
	s_mov_b64 s[34:35], 0
	v_add_f32_e32 v108, v108, v96
	v_add_f32_e32 v109, v109, v97
	v_max3_f32 v112, v110, v108, v109
	v_sub_f32_e32 v110, v142, v78
	v_sub_f32_e32 v111, v143, v79
	v_add_f32_e32 v110, v110, v98
	v_add_f32_e32 v111, v111, v99
	v_max3_f32 v114, v112, v110, v111
	v_sub_f32_e32 v112, v142, v80
	v_sub_f32_e32 v113, v143, v81
	v_add_f32_e32 v112, v112, v92
	v_add_f32_e32 v113, v113, v93
	v_max3_f32 v116, v114, v112, v113
	v_sub_f32_e32 v114, v142, v82
	v_sub_f32_e32 v115, v143, v83
	v_add_f32_e32 v114, v114, v94
	v_add_f32_e32 v115, v115, v95
	v_max3_f32 v118, v116, v114, v115
	v_sub_f32_e32 v116, v142, v72
	v_sub_f32_e32 v117, v143, v73
	v_add_f32_e32 v116, v116, v88
	v_add_f32_e32 v117, v117, v89
	v_max3_f32 v202, v118, v116, v117
	v_sub_f32_e32 v118, v142, v74
	v_sub_f32_e32 v119, v143, v75
	v_add_f32_e32 v118, v118, v90
	v_add_f32_e32 v119, v119, v91
	v_max3_f32 v230, v202, v118, v119

.LBB0_882:
	s_waitcnt lgkmcnt(0)
	v_max3_f32 v89, v227, v231, v232
	v_sub_f32_e32 v72, v227, v89
	v_exp_f32_e32 v88, v72
	v_sub_f32_e32 v72, v160, v89
	v_exp_f32_e32 v72, v72
	v_sub_f32_e32 v74, v161, v89
	v_exp_f32_e32 v74, v74
	v_sub_f32_e32 v75, v162, v89
	v_sub_f32_e32 v76, v163, v89
	v_exp_f32_e32 v75, v75
	v_exp_f32_e32 v77, v76
	v_sub_f32_e32 v76, v164, v89
	v_exp_f32_e32 v78, v76
	v_sub_f32_e32 v76, v165, v89
	v_add_f32_e32 v73, 0, v72
	v_exp_f32_e32 v79, v76
	v_sub_f32_e32 v76, v168, v89
	v_add_f32_e32 v73, v74, v73
	v_exp_f32_e32 v80, v76
	v_sub_f32_e32 v76, v169, v89
	v_add_f32_e32 v73, v75, v73
	v_exp_f32_e32 v81, v76
	v_add_f32_e32 v73, v77, v73
	v_cvt_pk_bf16_f32 v76, v72, v74
	v_sub_f32_e32 v72, v166, v89
	v_add_f32_e32 v73, v78, v73
	v_exp_f32_e32 v72, v72
	v_sub_f32_e32 v74, v167, v89
	v_add_f32_e32 v73, v79, v73
	v_cvt_pk_bf16_f32 v77, v75, v77
	v_exp_f32_e32 v74, v74
	v_sub_f32_e32 v75, v170, v89
	v_add_f32_e32 v73, v80, v73
	v_cvt_pk_bf16_f32 v78, v78, v79
	v_cvt_pk_bf16_f32 v79, v80, v81
	v_exp_f32_e32 v75, v75
	v_sub_f32_e32 v80, v171, v89
	v_add_f32_e32 v73, v81, v73
	v_exp_f32_e32 v80, v80
	v_sub_f32_e32 v81, v172, v89
	v_add_f32_e32 v73, v72, v73
	v_exp_f32_e32 v81, v81
	v_sub_f32_e32 v82, v173, v89
	v_add_f32_e32 v73, v74, v73
	v_exp_f32_e32 v82, v82
	v_sub_f32_e32 v83, v174, v89
	v_add_f32_e32 v73, v75, v73
	v_exp_f32_e32 v83, v83
	v_sub_f32_e32 v84, v175, v89
	v_add_f32_e32 v73, v80, v73
	v_exp_f32_e32 v84, v84
	v_add_f32_e32 v73, v81, v73
	v_add_f32_e32 v73, v82, v73
	v_add_f32_e32 v73, v83, v73
	v_add_f32_e32 v91, v84, v73
	v_cvt_pk_bf16_f32 v73, v75, v80
	ds_bpermute_b32 v80, v229, v230
	v_cvt_pk_bf16_f32 v72, v72, v74
	v_cvt_pk_bf16_f32 v74, v81, v82
	v_max_f32_e32 v81, v230, v230
	v_cvt_pk_bf16_f32 v75, v83, v84
	s_waitcnt lgkmcnt(0)
	v_max_f32_e32 v80, v80, v80
	v_max_f32_e32 v80, v81, v80
	ds_bpermute_b32 v81, v228, v80
	v_fmac_f32_e32 v91, v225, v88
	v_mul_f32_e32 v54, v54, v88
	v_mul_f32_e32 v55, v55, v88
	v_mul_f32_e32 v52, v52, v88
	v_mul_f32_e32 v53, v53, v88
	v_mul_f32_e32 v46, v46, v88
	v_mul_f32_e32 v47, v47, v88
	s_waitcnt lgkmcnt(0)
	v_max3_f32 v92, v226, v80, v81
	v_sub_f32_e32 v80, v226, v92
	v_exp_f32_e32 v90, v80
	v_sub_f32_e32 v80, v104, v92
	v_exp_f32_e32 v80, v80
	v_sub_f32_e32 v82, v105, v92
	v_exp_f32_e32 v82, v82
	v_sub_f32_e32 v83, v106, v92
	v_sub_f32_e32 v84, v107, v92
	v_exp_f32_e32 v83, v83
	v_exp_f32_e32 v85, v84
	v_sub_f32_e32 v84, v108, v92
	v_exp_f32_e32 v86, v84
	v_sub_f32_e32 v84, v109, v92
	v_add_f32_e32 v81, 0, v80
	v_exp_f32_e32 v87, v84
	v_sub_f32_e32 v84, v110, v92
	v_add_f32_e32 v81, v82, v81
	v_exp_f32_e32 v93, v84
	v_sub_f32_e32 v84, v111, v92
	v_add_f32_e32 v81, v83, v81
	v_exp_f32_e32 v94, v84
	v_add_f32_e32 v81, v85, v81
	v_cvt_pk_bf16_f32 v84, v80, v82
	v_sub_f32_e32 v80, v112, v92
	v_add_f32_e32 v81, v86, v81
	v_exp_f32_e32 v80, v80
	v_sub_f32_e32 v82, v113, v92
	v_add_f32_e32 v81, v87, v81
	v_cvt_pk_bf16_f32 v85, v83, v85
	v_exp_f32_e32 v82, v82
	v_sub_f32_e32 v83, v114, v92
	v_add_f32_e32 v81, v93, v81
	v_cvt_pk_bf16_f32 v86, v86, v87
	v_cvt_pk_bf16_f32 v87, v93, v94
	v_exp_f32_e32 v83, v83
	v_sub_f32_e32 v93, v115, v92
	v_add_f32_e32 v81, v94, v81
	v_exp_f32_e32 v94, v93
	v_sub_f32_e32 v93, v116, v92
	v_add_f32_e32 v81, v80, v81
	v_exp_f32_e32 v95, v93
	v_sub_f32_e32 v93, v117, v92
	v_add_f32_e32 v81, v82, v81
	v_exp_f32_e32 v96, v93
	v_sub_f32_e32 v93, v118, v92
	v_add_f32_e32 v81, v83, v81
	v_exp_f32_e32 v97, v93
	v_sub_f32_e32 v93, v119, v92
	v_add_f32_e32 v81, v94, v81
	v_exp_f32_e32 v98, v93
	v_add_f32_e32 v81, v95, v81
	v_add_f32_e32 v81, v96, v81
	v_add_f32_e32 v81, v97, v81
	v_add_f32_e32 v93, v98, v81
	v_cvt_pk_bf16_f32 v80, v80, v82
	v_cvt_pk_bf16_f32 v81, v83, v94
	v_cvt_pk_bf16_f32 v82, v95, v96
	v_cvt_pk_bf16_f32 v83, v97, v98
	ds_read_b128 v[94:97], v222 offset:9216
	v_mul_f32_e32 v38, v38, v90
	v_mul_f32_e32 v39, v39, v90
	v_mul_f32_e32 v36, v36, v90
	v_mul_f32_e32 v37, v37, v90
	s_waitcnt lgkmcnt(0)
	v_mfma_f32_16x16x32_bf16 v[52:55], v[94:97], v[76:79], v[52:55]
	v_mul_f32_e64 v44, v44, v88
	v_mul_f32_e64 v45, v45, v88
	v_mul_f32_e32 v30, v30, v90
	v_mul_f32_e32 v31, v31, v90
	v_mul_f32_e32 v28, v28, v90
	v_mul_f32_e32 v29, v29, v90
	v_mfma_f32_16x16x32_bf16 v[36:39], v[94:97], v[84:87], v[36:39]
	ds_read_b128 v[94:97], v222 offset:9280
	v_mul_f32_e32 v42, v42, v88
	v_mul_f32_e32 v43, v43, v88
	v_mul_f32_e32 v40, v40, v88
	v_mul_f32_e32 v41, v41, v88
	s_waitcnt lgkmcnt(0)
	v_mfma_f32_16x16x32_bf16 v[52:55], v[94:97], v[72:75], v[52:55]
	v_mul_f32_e64 v18, v18, v90
	v_mul_f32_e64 v19, v19, v90
	v_mul_f32_e32 v16, v16, v90
	v_mul_f32_e32 v17, v17, v90
	v_mul_f32_e32 v50, v50, v88
	v_mul_f32_e32 v51, v51, v88
	v_mfma_f32_16x16x32_bf16 v[36:39], v[94:97], v[80:83], v[36:39]
	ds_read_b128 v[94:97], v222 offset:11520
	v_mul_f32_e32 v48, v48, v88
	v_mul_f32_e32 v49, v49, v88
	v_mul_f32_e32 v34, v34, v90
	v_mul_f32_e32 v35, v35, v90
	s_waitcnt lgkmcnt(0)
	v_mfma_f32_16x16x32_bf16 v[44:47], v[94:97], v[76:79], v[44:47]
	v_mul_f32_e64 v32, v32, v90
	v_mul_f32_e64 v33, v33, v90
	v_fmac_f32_e32 v93, v224, v90
	v_mov_b32_e32 v226, v92
	v_mfma_f32_16x16x32_bf16 v[28:31], v[94:97], v[84:87], v[28:31]
	ds_read_b128 v[94:97], v222 offset:11584
	v_mov_b32_e32 v227, v89
	v_mov_b32_e32 v224, v93
	s_waitcnt lgkmcnt(0)
	v_mfma_f32_16x16x32_bf16 v[44:47], v[94:97], v[72:75], v[44:47]
	v_mov_b32_e32 v225, v91
	v_mfma_f32_16x16x32_bf16 v[28:31], v[94:97], v[80:83], v[28:31]
	ds_read_b128 v[94:97], v222 offset:13824
	s_waitcnt lgkmcnt(0)
	v_mfma_f32_16x16x32_bf16 v[40:43], v[94:97], v[76:79], v[40:43]
	v_mfma_f32_16x16x32_bf16 v[16:19], v[94:97], v[84:87], v[16:19]
	ds_read_b128 v[94:97], v222 offset:13888
	s_waitcnt lgkmcnt(0)
	v_mfma_f32_16x16x32_bf16 v[40:43], v[94:97], v[72:75], v[40:43]
	v_mfma_f32_16x16x32_bf16 v[16:19], v[94:97], v[80:83], v[16:19]
	ds_read_b128 v[94:97], v223 offset:9216
	s_waitcnt lgkmcnt(0)
	v_mfma_f32_16x16x32_bf16 v[48:51], v[94:97], v[76:79], v[48:51]
	ds_read_b128 v[76:79], v223 offset:9280
	v_mfma_f32_16x16x32_bf16 v[32:35], v[94:97], v[84:87], v[32:35]
	s_waitcnt lgkmcnt(0)
	v_mfma_f32_16x16x32_bf16 v[48:51], v[76:79], v[72:75], v[48:51]
	v_mfma_f32_16x16x32_bf16 v[32:35], v[76:79], v[80:83], v[32:35]
